# DIFF: next-tile summary (ttab) prefetched into SGPRs during P.V(sub 1)
# speedup vs baseline: 1.0115x; 1.0115x over previous
; #define MFMA(a, b, c) __builtin_amdgcn_mfma_f32_32x32x16_bf16((a), (b), (c), 0, 0, 0)
; DI u32 pk2(float a, float b) { f2_t v = {a, b}; bf2_t r = __builtin_convertvector(v, bf2_t); return __builtin_bit_cast(u32, r); }
; template <bool DIFF>
; DI void attn_phase(const AttnArgs& a, char* lds) {
;     ...
;       const int4 tinfo = *(const int4*)(ttab + 4 * t);
;       const int kcmin = __builtin_amdgcn_readfirstlane(tinfo.x), kcmax = __builtin_amdgcn_readfirstlane(tinfo.y);
;     ...
; #pragma unroll
;           for (int r = 0; r < 16; ++r) { s1[r] = __builtin_amdgcn_exp2f(s1[r]); ps += s1[r]; }
;           l_sum += ps;
;           asm volatile("" : "+v"(l_sum));
; #pragma unroll
;           for (int i = 0; i < 2 * NM; ++i) { __builtin_amdgcn_sched_group_barrier(0x008, 1, 0); __builtin_amdgcn_sched_group_barrier(0x002, 4, 0); }
;         }
;         __builtin_amdgcn_sched_barrier(0);
;         {
; #pragma unroll
;           for (int s2 = 0; s2 < 2; ++s2) {
;             bf16x8 vf[NM];
; #pragma unroll
;             for (int m = 0; m < NM; ++m) vf[m] = *(const bf16x8*)(sb + voffb + m * 4096 + (((4 + 2 * s2) ^ vx) << 4));
;             u32x4 pw;
;             pw[0] = pk2(s1[8 * s2], s1[8 * s2 + 1]); pw[1] = pk2(s1[8 * s2 + 2], s1[8 * s2 + 3]);
;             pw[2] = pk2(s1[8 * s2 + 4], s1[8 * s2 + 5]); pw[3] = pk2(s1[8 * s2 + 6], s1[8 * s2 + 7]);
;             const bf16x8 pf = __builtin_bit_cast(bf16x8, pw);
; #pragma unroll
;             for (int m = 0; m < NM; ++m) o[m] = MFMA(vf[m], pf, o[m]);
;           }
;         }
.LBB0_607:
	v_exp_f32_e32 v0, v164
	v_exp_f32_e32 v9, v165
	v_exp_f32_e32 v144, v166
	v_exp_f32_e32 v146, v167
	v_add_f32_e32 v2, 0, v0
	v_exp_f32_e32 v147, v168
	v_add_f32_e32 v2, v9, v2
	v_exp_f32_e32 v148, v169
	v_add_f32_e32 v2, v144, v2
	v_exp_f32_e32 v149, v170
	v_add_f32_e32 v2, v146, v2
	v_exp_f32_e32 v150, v171
	v_add_f32_e32 v2, v147, v2
	v_exp_f32_e32 v151, v172
	v_add_f32_e32 v2, v148, v2
	v_exp_f32_e32 v145, v173
	v_add_f32_e32 v2, v149, v2
	v_exp_f32_e32 v152, v174
	v_add_f32_e32 v2, v150, v2
	v_exp_f32_e32 v153, v175
	v_add_f32_e32 v2, v151, v2
	v_exp_f32_e32 v154, v248
	v_add_f32_e32 v2, v145, v2
	v_exp_f32_e32 v155, v249
	v_add_f32_e32 v2, v152, v2
	v_exp_f32_e32 v14, v250
	v_add_f32_e32 v2, v153, v2
	v_exp_f32_e32 v15, v251
	v_add_f32_e32 v2, v154, v2
	v_add_f32_e32 v2, v155, v2
	v_add_f32_e32 v2, v14, v2
	v_add_f32_e32 v2, v15, v2
	v_add_f32_e32 v226, v162, v2
	s_add_i32 s87, s80, 16
	v_mov_b32_e32 v164, s87
	ds_read_b128 v[164:167], v164
	v_xad_u32 v156, v161, 64, v160
	ds_read_b128 v[2:5], v156 offset:32768
	ds_read_b128 v[228:231], v156 offset:36864
	ds_read_b128 v[232:235], v156 offset:40960
	ds_read_b128 v[236:239], v156 offset:45056
	ds_read_b128 v[240:243], v156 offset:49152
	ds_read_b128 v[244:247], v156 offset:53248
	ds_read_b128 v[248:251], v156 offset:57344
	v_cvt_pk_bf16_f32 v6, v0, v9
	v_cvt_pk_bf16_f32 v7, v144, v146
	v_cvt_pk_bf16_f32 v8, v147, v148
	v_cvt_pk_bf16_f32 v9, v149, v150
	v_xad_u32 v0, v161, s74, v160
	v_cvt_pk_bf16_f32 v10, v151, v145
	v_cvt_pk_bf16_f32 v11, v152, v153
	v_cvt_pk_bf16_f32 v12, v154, v155
	v_cvt_pk_bf16_f32 v13, v14, v15
	s_waitcnt lgkmcnt(6)
	v_mfma_f32_32x32x16_bf16 v[128:143], v[2:5], v[6:9], v[128:143]
	ds_read_b128 v[2:5], v156 offset:61440
	v_readfirstlane_b32 s32, v164
	v_readfirstlane_b32 s87, v165
	v_readfirstlane_b32 s88, v166
	v_readfirstlane_b32 s89, v167
	s_waitcnt lgkmcnt(6)
	v_mfma_f32_32x32x16_bf16 v[112:127], v[228:231], v[6:9], v[112:127]
	ds_read_b128 v[228:231], v0 offset:32768
	s_waitcnt lgkmcnt(6)
	v_mfma_f32_32x32x16_bf16 v[96:111], v[232:235], v[6:9], v[96:111]
	ds_read_b128 v[232:235], v0 offset:36864
	s_waitcnt lgkmcnt(6)
	v_mfma_f32_32x32x16_bf16 v[80:95], v[236:239], v[6:9], v[80:95]
	ds_read_b128 v[236:239], v0 offset:40960
	s_waitcnt lgkmcnt(6)
	v_mfma_f32_32x32x16_bf16 v[64:79], v[240:243], v[6:9], v[64:79]
	ds_read_b128 v[240:243], v0 offset:45056
	s_waitcnt lgkmcnt(6)
	v_mfma_f32_32x32x16_bf16 v[48:63], v[244:247], v[6:9], v[48:63]
	ds_read_b128 v[244:247], v0 offset:49152
	s_waitcnt lgkmcnt(6)
	v_mfma_f32_32x32x16_bf16 v[32:47], v[248:251], v[6:9], v[32:47]
	ds_read_b128 v[248:251], v0 offset:53248
	s_waitcnt lgkmcnt(6)
	v_mfma_f32_32x32x16_bf16 v[16:31], v[2:5], v[6:9], v[16:31]
	ds_read_b128 v[2:5], v0 offset:57344
	s_waitcnt lgkmcnt(6)
	v_mfma_f32_32x32x16_bf16 v[128:143], v[228:231], v[10:13], v[128:143]
	ds_read_b128 v[228:231], v0 offset:61440
	s_waitcnt lgkmcnt(6)
	v_mfma_f32_32x32x16_bf16 v[112:127], v[232:235], v[10:13], v[112:127]
	s_waitcnt lgkmcnt(5)
	v_mfma_f32_32x32x16_bf16 v[96:111], v[236:239], v[10:13], v[96:111]
	s_waitcnt lgkmcnt(4)
	v_mfma_f32_32x32x16_bf16 v[80:95], v[240:243], v[10:13], v[80:95]
	s_waitcnt lgkmcnt(3)
	v_mfma_f32_32x32x16_bf16 v[64:79], v[244:247], v[10:13], v[64:79]
	s_waitcnt lgkmcnt(2)
	v_mfma_f32_32x32x16_bf16 v[48:63], v[248:251], v[10:13], v[48:63]
	s_waitcnt lgkmcnt(1)
	v_mfma_f32_32x32x16_bf16 v[32:47], v[2:5], v[10:13], v[32:47]
	s_waitcnt lgkmcnt(0)
	v_mfma_f32_32x32x16_bf16 v[16:31], v[228:231], v[10:13], v[16:31]
